# attention softmax with packed f32 ops: v_pk_fma for the scale/shift before exp2 and v_pk_add for the row sum
# speedup vs baseline: 1.0013x; 1.0013x over previous
.Lam_keep_a:
	v_mul_f32_e32 v243, 0xbe0293ee, v238
	v_mov_b32_e32 v242, 0x3e0293ee
	v_pk_fma_f32 v[162:163], v[162:163], v[242:243], v[242:243] op_sel:[0,0,1] op_sel_hi:[1,0,1]
	v_pk_fma_f32 v[164:165], v[164:165], v[242:243], v[242:243] op_sel:[0,0,1] op_sel_hi:[1,0,1]
	v_pk_fma_f32 v[166:167], v[166:167], v[242:243], v[242:243] op_sel:[0,0,1] op_sel_hi:[1,0,1]
	v_pk_fma_f32 v[168:169], v[168:169], v[242:243], v[242:243] op_sel:[0,0,1] op_sel_hi:[1,0,1]
	v_pk_fma_f32 v[170:171], v[170:171], v[242:243], v[242:243] op_sel:[0,0,1] op_sel_hi:[1,0,1]
	v_pk_fma_f32 v[172:173], v[172:173], v[242:243], v[242:243] op_sel:[0,0,1] op_sel_hi:[1,0,1]
	v_pk_fma_f32 v[174:175], v[174:175], v[242:243], v[242:243] op_sel:[0,0,1] op_sel_hi:[1,0,1]
	v_pk_fma_f32 v[176:177], v[176:177], v[242:243], v[242:243] op_sel:[0,0,1] op_sel_hi:[1,0,1]
	v_pk_fma_f32 v[178:179], v[178:179], v[242:243], v[242:243] op_sel:[0,0,1] op_sel_hi:[1,0,1]
	v_pk_fma_f32 v[180:181], v[180:181], v[242:243], v[242:243] op_sel:[0,0,1] op_sel_hi:[1,0,1]
	v_pk_fma_f32 v[182:183], v[182:183], v[242:243], v[242:243] op_sel:[0,0,1] op_sel_hi:[1,0,1]
	v_pk_fma_f32 v[184:185], v[184:185], v[242:243], v[242:243] op_sel:[0,0,1] op_sel_hi:[1,0,1]
	v_pk_fma_f32 v[186:187], v[186:187], v[242:243], v[242:243] op_sel:[0,0,1] op_sel_hi:[1,0,1]
	v_pk_fma_f32 v[188:189], v[188:189], v[242:243], v[242:243] op_sel:[0,0,1] op_sel_hi:[1,0,1]
	v_pk_fma_f32 v[190:191], v[190:191], v[242:243], v[242:243] op_sel:[0,0,1] op_sel_hi:[1,0,1]
	v_pk_fma_f32 v[192:193], v[192:193], v[242:243], v[242:243] op_sel:[0,0,1] op_sel_hi:[1,0,1]
	v_exp_f32_e32 v162, v162
	v_exp_f32_e32 v163, v163
	v_exp_f32_e32 v164, v164
	v_exp_f32_e32 v165, v165
	v_exp_f32_e32 v166, v166
	v_exp_f32_e32 v167, v167
	v_exp_f32_e32 v168, v168
	v_exp_f32_e32 v169, v169
	v_exp_f32_e32 v170, v170
	v_exp_f32_e32 v171, v171
	v_exp_f32_e32 v172, v172
	v_exp_f32_e32 v173, v173
	v_exp_f32_e32 v174, v174
	v_exp_f32_e32 v175, v175
	v_exp_f32_e32 v176, v176
	v_exp_f32_e32 v177, v177
	v_exp_f32_e32 v178, v178
	v_exp_f32_e32 v179, v179
	v_exp_f32_e32 v180, v180
	v_exp_f32_e32 v181, v181
	v_exp_f32_e32 v182, v182
	v_exp_f32_e32 v183, v183
	v_exp_f32_e32 v184, v184
	v_exp_f32_e32 v185, v185
	v_exp_f32_e32 v186, v186
	v_exp_f32_e32 v187, v187
	v_exp_f32_e32 v188, v188
	v_exp_f32_e32 v189, v189
	v_exp_f32_e32 v190, v190
	v_exp_f32_e32 v191, v191
	v_exp_f32_e32 v192, v192
	v_exp_f32_e32 v193, v193
	v_pk_add_f32 v[240:241], v[162:163], v[164:165]
	v_pk_add_f32 v[240:241], v[240:241], v[166:167]
	v_pk_add_f32 v[240:241], v[240:241], v[168:169]
	v_pk_add_f32 v[240:241], v[240:241], v[170:171]
	v_pk_add_f32 v[240:241], v[240:241], v[172:173]
	v_pk_add_f32 v[240:241], v[240:241], v[174:175]
	v_pk_add_f32 v[240:241], v[240:241], v[176:177]
	v_pk_add_f32 v[240:241], v[240:241], v[178:179]
	v_pk_add_f32 v[240:241], v[240:241], v[180:181]
	v_pk_add_f32 v[240:241], v[240:241], v[182:183]
	v_pk_add_f32 v[240:241], v[240:241], v[184:185]
	v_pk_add_f32 v[240:241], v[240:241], v[186:187]
	v_pk_add_f32 v[240:241], v[240:241], v[188:189]
	v_pk_add_f32 v[240:241], v[240:241], v[190:191]
	v_pk_add_f32 v[240:241], v[240:241], v[192:193]
	v_add_f32_e32 v240, v240, v241
	v_mov_b32_e32 v241, v240
	v_cvt_pk_bf16_f32 v196, v162, v163
	v_cvt_pk_bf16_f32 v197, v164, v165
	v_cvt_pk_bf16_f32 v198, v166, v167
	v_cvt_pk_bf16_f32 v199, v168, v169
	v_cvt_pk_bf16_f32 v200, v170, v171
	v_cvt_pk_bf16_f32 v201, v172, v173
	v_cvt_pk_bf16_f32 v202, v174, v175
	v_cvt_pk_bf16_f32 v203, v176, v177
	v_cvt_pk_bf16_f32 v204, v178, v179
	v_cvt_pk_bf16_f32 v205, v180, v181
	v_cvt_pk_bf16_f32 v206, v182, v183
	v_cvt_pk_bf16_f32 v207, v184, v185
	v_cvt_pk_bf16_f32 v208, v186, v187
	v_cvt_pk_bf16_f32 v209, v188, v189
	v_cvt_pk_bf16_f32 v210, v190, v191
	v_cvt_pk_bf16_f32 v211, v192, v193
	s_nop 1
	v_permlane32_swap_b32_e32 v240, v241
	v_permlane32_swap_b32_e32 v196, v198
	v_permlane32_swap_b32_e32 v197, v199
	v_permlane32_swap_b32_e32 v200, v202
	v_permlane32_swap_b32_e32 v201, v203
	v_permlane32_swap_b32_e32 v204, v206
	v_permlane32_swap_b32_e32 v205, v207
	v_permlane32_swap_b32_e32 v208, v210
	v_permlane32_swap_b32_e32 v209, v211
	v_add_f32_e32 v240, v240, v241
	v_add_f32_e32 v239, v239, v240
	ds_read_b64_tr_b16 v[162:163], v236 offset:0
	ds_read_b64_tr_b16 v[164:165], v236 offset:4096
	ds_read_b64_tr_b16 v[166:167], v236 offset:8192
	ds_read_b64_tr_b16 v[168:169], v236 offset:12288
	ds_read_b64_tr_b16 v[170:171], v236 offset:16384
	ds_read_b64_tr_b16 v[172:173], v236 offset:20480
	ds_read_b64_tr_b16 v[174:175], v236 offset:24576
	ds_read_b64_tr_b16 v[176:177], v236 offset:28672
	ds_read_b64_tr_b16 v[178:179], v236 offset:512
	ds_read_b64_tr_b16 v[180:181], v236 offset:4608
	ds_read_b64_tr_b16 v[182:183], v236 offset:8704
	ds_read_b64_tr_b16 v[184:185], v236 offset:12800
	ds_read_b64_tr_b16 v[186:187], v236 offset:16896
	ds_read_b64_tr_b16 v[188:189], v236 offset:20992
	ds_read_b64_tr_b16 v[190:191], v236 offset:25088
	ds_read_b64_tr_b16 v[192:193], v236 offset:29184
	s_waitcnt lgkmcnt(8)
	v_mfma_f32_32x32x16_bf16 v[0:15], v[196:199], v[162:165], v[0:15]
	v_mfma_f32_32x32x16_bf16 v[0:15], v[200:203], v[166:169], v[0:15]
	v_mfma_f32_32x32x16_bf16 v[0:15], v[204:207], v[170:173], v[0:15]
	v_mfma_f32_32x32x16_bf16 v[0:15], v[208:211], v[174:177], v[0:15]
	ds_read_b64_tr_b16 v[162:163], v236 offset:1024
	ds_read_b64_tr_b16 v[164:165], v236 offset:5120
	ds_read_b64_tr_b16 v[166:167], v236 offset:9216
	ds_read_b64_tr_b16 v[168:169], v236 offset:13312
	ds_read_b64_tr_b16 v[170:171], v236 offset:17408
	ds_read_b64_tr_b16 v[172:173], v236 offset:21504
	ds_read_b64_tr_b16 v[174:175], v236 offset:25600
	ds_read_b64_tr_b16 v[176:177], v236 offset:29696
	s_waitcnt lgkmcnt(8)
	v_mfma_f32_32x32x16_bf16 v[16:31], v[196:199], v[178:181], v[16:31]
	v_mfma_f32_32x32x16_bf16 v[16:31], v[200:203], v[182:185], v[16:31]
	v_mfma_f32_32x32x16_bf16 v[16:31], v[204:207], v[186:189], v[16:31]
	v_mfma_f32_32x32x16_bf16 v[16:31], v[208:211], v[190:193], v[16:31]
	ds_read_b64_tr_b16 v[178:179], v236 offset:1536
	ds_read_b64_tr_b16 v[180:181], v236 offset:5632
	ds_read_b64_tr_b16 v[182:183], v236 offset:9728
	ds_read_b64_tr_b16 v[184:185], v236 offset:13824
	ds_read_b64_tr_b16 v[186:187], v236 offset:17920
	ds_read_b64_tr_b16 v[188:189], v236 offset:22016
	ds_read_b64_tr_b16 v[190:191], v236 offset:26112
	ds_read_b64_tr_b16 v[192:193], v236 offset:30208
	s_waitcnt lgkmcnt(8)
	v_mfma_f32_32x32x16_bf16 v[32:47], v[196:199], v[162:165], v[32:47]
	v_mfma_f32_32x32x16_bf16 v[32:47], v[200:203], v[166:169], v[32:47]
	v_mfma_f32_32x32x16_bf16 v[32:47], v[204:207], v[170:173], v[32:47]
	v_mfma_f32_32x32x16_bf16 v[32:47], v[208:211], v[174:177], v[32:47]
	ds_read_b64_tr_b16 v[162:163], v236 offset:2048
	ds_read_b64_tr_b16 v[164:165], v236 offset:6144
	ds_read_b64_tr_b16 v[166:167], v236 offset:10240
	ds_read_b64_tr_b16 v[168:169], v236 offset:14336
	ds_read_b64_tr_b16 v[170:171], v236 offset:18432
	ds_read_b64_tr_b16 v[172:173], v236 offset:22528
	ds_read_b64_tr_b16 v[174:175], v236 offset:26624
	ds_read_b64_tr_b16 v[176:177], v236 offset:30720
	s_waitcnt lgkmcnt(8)
	v_mfma_f32_32x32x16_bf16 v[48:63], v[196:199], v[178:181], v[48:63]
	v_mfma_f32_32x32x16_bf16 v[48:63], v[200:203], v[182:185], v[48:63]
	v_mfma_f32_32x32x16_bf16 v[48:63], v[204:207], v[186:189], v[48:63]
	v_mfma_f32_32x32x16_bf16 v[48:63], v[208:211], v[190:193], v[48:63]
	ds_read_b64_tr_b16 v[178:179], v236 offset:2560
	ds_read_b64_tr_b16 v[180:181], v236 offset:6656
	ds_read_b64_tr_b16 v[182:183], v236 offset:10752
	ds_read_b64_tr_b16 v[184:185], v236 offset:14848
	ds_read_b64_tr_b16 v[186:187], v236 offset:18944
	ds_read_b64_tr_b16 v[188:189], v236 offset:23040
	ds_read_b64_tr_b16 v[190:191], v236 offset:27136
	ds_read_b64_tr_b16 v[192:193], v236 offset:31232
	s_waitcnt lgkmcnt(8)
	v_mfma_f32_32x32x16_bf16 v[64:79], v[196:199], v[162:165], v[64:79]
	v_mfma_f32_32x32x16_bf16 v[64:79], v[200:203], v[166:169], v[64:79]
	v_mfma_f32_32x32x16_bf16 v[64:79], v[204:207], v[170:173], v[64:79]
	v_mfma_f32_32x32x16_bf16 v[64:79], v[208:211], v[174:177], v[64:79]
	ds_read_b64_tr_b16 v[162:163], v236 offset:3072
	ds_read_b64_tr_b16 v[164:165], v236 offset:7168
	ds_read_b64_tr_b16 v[166:167], v236 offset:11264
	ds_read_b64_tr_b16 v[168:169], v236 offset:15360
	ds_read_b64_tr_b16 v[170:171], v236 offset:19456
	ds_read_b64_tr_b16 v[172:173], v236 offset:23552
	ds_read_b64_tr_b16 v[174:175], v236 offset:27648
	ds_read_b64_tr_b16 v[176:177], v236 offset:31744
	s_waitcnt lgkmcnt(8)
	v_mfma_f32_32x32x16_bf16 v[80:95], v[196:199], v[178:181], v[80:95]
	v_mfma_f32_32x32x16_bf16 v[80:95], v[200:203], v[182:185], v[80:95]
	v_mfma_f32_32x32x16_bf16 v[80:95], v[204:207], v[186:189], v[80:95]
	v_mfma_f32_32x32x16_bf16 v[80:95], v[208:211], v[190:193], v[80:95]
	ds_read_b64_tr_b16 v[178:179], v236 offset:3584
	ds_read_b64_tr_b16 v[180:181], v236 offset:7680
	ds_read_b64_tr_b16 v[182:183], v236 offset:11776
	ds_read_b64_tr_b16 v[184:185], v236 offset:15872
	ds_read_b64_tr_b16 v[186:187], v236 offset:19968
	ds_read_b64_tr_b16 v[188:189], v236 offset:24064
	ds_read_b64_tr_b16 v[190:191], v236 offset:28160
	ds_read_b64_tr_b16 v[192:193], v236 offset:32256
	s_waitcnt lgkmcnt(8)
	v_mfma_f32_32x32x16_bf16 v[98:113], v[196:199], v[162:165], v[98:113]
	v_mfma_f32_32x32x16_bf16 v[98:113], v[200:203], v[166:169], v[98:113]
	v_mfma_f32_32x32x16_bf16 v[98:113], v[204:207], v[170:173], v[98:113]
	v_mfma_f32_32x32x16_bf16 v[98:113], v[208:211], v[174:177], v[98:113]
	s_waitcnt lgkmcnt(0)
	v_mfma_f32_32x32x16_bf16 v[114:129], v[196:199], v[178:181], v[114:129]
	v_mfma_f32_32x32x16_bf16 v[114:129], v[200:203], v[182:185], v[114:129]
	v_mfma_f32_32x32x16_bf16 v[114:129], v[204:207], v[186:189], v[114:129]
	v_mfma_f32_32x32x16_bf16 v[114:129], v[208:211], v[190:193], v[114:129]
	s_waitcnt vmcnt(0)
	s_barrier
	s_cmp_le_u32 s13, 2
	s_cbranch_scc1 .Lam_nodma_a
	s_add_i32 m0, s39, 0x0
	s_nop 0
	global_load_lds_dwordx4 v244, s[18:19]
	s_add_i32 m0, s39, 0x400
	s_nop 0
	global_load_lds_dwordx4 v245, s[18:19]
	s_add_i32 m0, s47, 0x0
	s_nop 0
	global_load_lds_dwordx4 v246, s[20:21]
	s_add_i32 m0, s47, 0x400
	s_nop 0
	global_load_lds_dwordx4 v247, s[20:21]
	s_add_i32 m0, s47, 0x800
	s_nop 0
	global_load_lds_dwordx4 v248, s[20:21]
	s_add_i32 m0, s47, 0xc00
	s_nop 0
	global_load_lds_dwordx4 v249, s[20:21]
	s_add_u32 s18, s18, 0x40000
	s_addc_u32 s19, s19, 0
	s_add_u32 s20, s20, 0x40000
	s_addc_u32 s21, s21, 0

.Lam_keep_b:
	v_mul_f32_e32 v243, 0xbe0293ee, v238
	v_mov_b32_e32 v242, 0x3e0293ee
	v_pk_fma_f32 v[162:163], v[162:163], v[242:243], v[242:243] op_sel:[0,0,1] op_sel_hi:[1,0,1]
	v_pk_fma_f32 v[164:165], v[164:165], v[242:243], v[242:243] op_sel:[0,0,1] op_sel_hi:[1,0,1]
	v_pk_fma_f32 v[166:167], v[166:167], v[242:243], v[242:243] op_sel:[0,0,1] op_sel_hi:[1,0,1]
	v_pk_fma_f32 v[168:169], v[168:169], v[242:243], v[242:243] op_sel:[0,0,1] op_sel_hi:[1,0,1]
	v_pk_fma_f32 v[170:171], v[170:171], v[242:243], v[242:243] op_sel:[0,0,1] op_sel_hi:[1,0,1]
	v_pk_fma_f32 v[172:173], v[172:173], v[242:243], v[242:243] op_sel:[0,0,1] op_sel_hi:[1,0,1]
	v_pk_fma_f32 v[174:175], v[174:175], v[242:243], v[242:243] op_sel:[0,0,1] op_sel_hi:[1,0,1]
	v_pk_fma_f32 v[176:177], v[176:177], v[242:243], v[242:243] op_sel:[0,0,1] op_sel_hi:[1,0,1]
	v_pk_fma_f32 v[178:179], v[178:179], v[242:243], v[242:243] op_sel:[0,0,1] op_sel_hi:[1,0,1]
	v_pk_fma_f32 v[180:181], v[180:181], v[242:243], v[242:243] op_sel:[0,0,1] op_sel_hi:[1,0,1]
	v_pk_fma_f32 v[182:183], v[182:183], v[242:243], v[242:243] op_sel:[0,0,1] op_sel_hi:[1,0,1]
	v_pk_fma_f32 v[184:185], v[184:185], v[242:243], v[242:243] op_sel:[0,0,1] op_sel_hi:[1,0,1]
	v_pk_fma_f32 v[186:187], v[186:187], v[242:243], v[242:243] op_sel:[0,0,1] op_sel_hi:[1,0,1]
	v_pk_fma_f32 v[188:189], v[188:189], v[242:243], v[242:243] op_sel:[0,0,1] op_sel_hi:[1,0,1]
	v_pk_fma_f32 v[190:191], v[190:191], v[242:243], v[242:243] op_sel:[0,0,1] op_sel_hi:[1,0,1]
	v_pk_fma_f32 v[192:193], v[192:193], v[242:243], v[242:243] op_sel:[0,0,1] op_sel_hi:[1,0,1]
	v_exp_f32_e32 v162, v162
	v_exp_f32_e32 v163, v163
	v_exp_f32_e32 v164, v164
	v_exp_f32_e32 v165, v165
	v_exp_f32_e32 v166, v166
	v_exp_f32_e32 v167, v167
	v_exp_f32_e32 v168, v168
	v_exp_f32_e32 v169, v169
	v_exp_f32_e32 v170, v170
	v_exp_f32_e32 v171, v171
	v_exp_f32_e32 v172, v172
	v_exp_f32_e32 v173, v173
	v_exp_f32_e32 v174, v174
	v_exp_f32_e32 v175, v175
	v_exp_f32_e32 v176, v176
	v_exp_f32_e32 v177, v177
	v_exp_f32_e32 v178, v178
	v_exp_f32_e32 v179, v179
	v_exp_f32_e32 v180, v180
	v_exp_f32_e32 v181, v181
	v_exp_f32_e32 v182, v182
	v_exp_f32_e32 v183, v183
	v_exp_f32_e32 v184, v184
	v_exp_f32_e32 v185, v185
	v_exp_f32_e32 v186, v186
	v_exp_f32_e32 v187, v187
	v_exp_f32_e32 v188, v188
	v_exp_f32_e32 v189, v189
	v_exp_f32_e32 v190, v190
	v_exp_f32_e32 v191, v191
	v_exp_f32_e32 v192, v192
	v_exp_f32_e32 v193, v193
	v_pk_add_f32 v[240:241], v[162:163], v[164:165]
	v_pk_add_f32 v[240:241], v[240:241], v[166:167]
	v_pk_add_f32 v[240:241], v[240:241], v[168:169]
	v_pk_add_f32 v[240:241], v[240:241], v[170:171]
	v_pk_add_f32 v[240:241], v[240:241], v[172:173]
	v_pk_add_f32 v[240:241], v[240:241], v[174:175]
	v_pk_add_f32 v[240:241], v[240:241], v[176:177]
	v_pk_add_f32 v[240:241], v[240:241], v[178:179]
	v_pk_add_f32 v[240:241], v[240:241], v[180:181]
	v_pk_add_f32 v[240:241], v[240:241], v[182:183]
	v_pk_add_f32 v[240:241], v[240:241], v[184:185]
	v_pk_add_f32 v[240:241], v[240:241], v[186:187]
	v_pk_add_f32 v[240:241], v[240:241], v[188:189]
	v_pk_add_f32 v[240:241], v[240:241], v[190:191]
	v_pk_add_f32 v[240:241], v[240:241], v[192:193]
	v_add_f32_e32 v240, v240, v241
	v_mov_b32_e32 v241, v240
	v_cvt_pk_bf16_f32 v196, v162, v163
	v_cvt_pk_bf16_f32 v197, v164, v165
	v_cvt_pk_bf16_f32 v198, v166, v167
	v_cvt_pk_bf16_f32 v199, v168, v169
	v_cvt_pk_bf16_f32 v200, v170, v171
	v_cvt_pk_bf16_f32 v201, v172, v173
	v_cvt_pk_bf16_f32 v202, v174, v175
	v_cvt_pk_bf16_f32 v203, v176, v177
	v_cvt_pk_bf16_f32 v204, v178, v179
	v_cvt_pk_bf16_f32 v205, v180, v181
	v_cvt_pk_bf16_f32 v206, v182, v183
	v_cvt_pk_bf16_f32 v207, v184, v185
	v_cvt_pk_bf16_f32 v208, v186, v187
	v_cvt_pk_bf16_f32 v209, v188, v189
	v_cvt_pk_bf16_f32 v210, v190, v191
	v_cvt_pk_bf16_f32 v211, v192, v193
	s_nop 1
	v_permlane32_swap_b32_e32 v240, v241
	v_permlane32_swap_b32_e32 v196, v198
	v_permlane32_swap_b32_e32 v197, v199
	v_permlane32_swap_b32_e32 v200, v202
	v_permlane32_swap_b32_e32 v201, v203
	v_permlane32_swap_b32_e32 v204, v206
	v_permlane32_swap_b32_e32 v205, v207
	v_permlane32_swap_b32_e32 v208, v210
	v_permlane32_swap_b32_e32 v209, v211
	v_add_f32_e32 v240, v240, v241
	v_add_f32_e32 v239, v239, v240
	ds_read_b64_tr_b16 v[162:163], v237 offset:0
	ds_read_b64_tr_b16 v[164:165], v237 offset:4096
	ds_read_b64_tr_b16 v[166:167], v237 offset:8192
	ds_read_b64_tr_b16 v[168:169], v237 offset:12288
	ds_read_b64_tr_b16 v[170:171], v237 offset:16384
	ds_read_b64_tr_b16 v[172:173], v237 offset:20480
	ds_read_b64_tr_b16 v[174:175], v237 offset:24576
	ds_read_b64_tr_b16 v[176:177], v237 offset:28672
	ds_read_b64_tr_b16 v[178:179], v237 offset:512
	ds_read_b64_tr_b16 v[180:181], v237 offset:4608
	ds_read_b64_tr_b16 v[182:183], v237 offset:8704
	ds_read_b64_tr_b16 v[184:185], v237 offset:12800
	ds_read_b64_tr_b16 v[186:187], v237 offset:16896
	ds_read_b64_tr_b16 v[188:189], v237 offset:20992
	ds_read_b64_tr_b16 v[190:191], v237 offset:25088
	ds_read_b64_tr_b16 v[192:193], v237 offset:29184
	s_waitcnt lgkmcnt(8)
	v_mfma_f32_32x32x16_bf16 v[0:15], v[196:199], v[162:165], v[0:15]
	v_mfma_f32_32x32x16_bf16 v[0:15], v[200:203], v[166:169], v[0:15]
	v_mfma_f32_32x32x16_bf16 v[0:15], v[204:207], v[170:173], v[0:15]
	v_mfma_f32_32x32x16_bf16 v[0:15], v[208:211], v[174:177], v[0:15]
	ds_read_b64_tr_b16 v[162:163], v237 offset:1024
	ds_read_b64_tr_b16 v[164:165], v237 offset:5120
	ds_read_b64_tr_b16 v[166:167], v237 offset:9216
	ds_read_b64_tr_b16 v[168:169], v237 offset:13312
	ds_read_b64_tr_b16 v[170:171], v237 offset:17408
	ds_read_b64_tr_b16 v[172:173], v237 offset:21504
	ds_read_b64_tr_b16 v[174:175], v237 offset:25600
	ds_read_b64_tr_b16 v[176:177], v237 offset:29696
	s_waitcnt lgkmcnt(8)
	v_mfma_f32_32x32x16_bf16 v[16:31], v[196:199], v[178:181], v[16:31]
	v_mfma_f32_32x32x16_bf16 v[16:31], v[200:203], v[182:185], v[16:31]
	v_mfma_f32_32x32x16_bf16 v[16:31], v[204:207], v[186:189], v[16:31]
	v_mfma_f32_32x32x16_bf16 v[16:31], v[208:211], v[190:193], v[16:31]
	ds_read_b64_tr_b16 v[178:179], v237 offset:1536
	ds_read_b64_tr_b16 v[180:181], v237 offset:5632
	ds_read_b64_tr_b16 v[182:183], v237 offset:9728
	ds_read_b64_tr_b16 v[184:185], v237 offset:13824
	ds_read_b64_tr_b16 v[186:187], v237 offset:17920
	ds_read_b64_tr_b16 v[188:189], v237 offset:22016
	ds_read_b64_tr_b16 v[190:191], v237 offset:26112
	ds_read_b64_tr_b16 v[192:193], v237 offset:30208
	s_waitcnt lgkmcnt(8)
	v_mfma_f32_32x32x16_bf16 v[32:47], v[196:199], v[162:165], v[32:47]
	v_mfma_f32_32x32x16_bf16 v[32:47], v[200:203], v[166:169], v[32:47]
	v_mfma_f32_32x32x16_bf16 v[32:47], v[204:207], v[170:173], v[32:47]
	v_mfma_f32_32x32x16_bf16 v[32:47], v[208:211], v[174:177], v[32:47]
	ds_read_b64_tr_b16 v[162:163], v237 offset:2048
	ds_read_b64_tr_b16 v[164:165], v237 offset:6144
	ds_read_b64_tr_b16 v[166:167], v237 offset:10240
	ds_read_b64_tr_b16 v[168:169], v237 offset:14336
	ds_read_b64_tr_b16 v[170:171], v237 offset:18432
	ds_read_b64_tr_b16 v[172:173], v237 offset:22528
	ds_read_b64_tr_b16 v[174:175], v237 offset:26624
	ds_read_b64_tr_b16 v[176:177], v237 offset:30720
	s_waitcnt lgkmcnt(8)
	v_mfma_f32_32x32x16_bf16 v[48:63], v[196:199], v[178:181], v[48:63]
	v_mfma_f32_32x32x16_bf16 v[48:63], v[200:203], v[182:185], v[48:63]
	v_mfma_f32_32x32x16_bf16 v[48:63], v[204:207], v[186:189], v[48:63]
	v_mfma_f32_32x32x16_bf16 v[48:63], v[208:211], v[190:193], v[48:63]
	ds_read_b64_tr_b16 v[178:179], v237 offset:2560
	ds_read_b64_tr_b16 v[180:181], v237 offset:6656
	ds_read_b64_tr_b16 v[182:183], v237 offset:10752
	ds_read_b64_tr_b16 v[184:185], v237 offset:14848
	ds_read_b64_tr_b16 v[186:187], v237 offset:18944
	ds_read_b64_tr_b16 v[188:189], v237 offset:23040
	ds_read_b64_tr_b16 v[190:191], v237 offset:27136
	ds_read_b64_tr_b16 v[192:193], v237 offset:31232
	s_waitcnt lgkmcnt(8)
	v_mfma_f32_32x32x16_bf16 v[64:79], v[196:199], v[162:165], v[64:79]
	v_mfma_f32_32x32x16_bf16 v[64:79], v[200:203], v[166:169], v[64:79]
	v_mfma_f32_32x32x16_bf16 v[64:79], v[204:207], v[170:173], v[64:79]
	v_mfma_f32_32x32x16_bf16 v[64:79], v[208:211], v[174:177], v[64:79]
	ds_read_b64_tr_b16 v[162:163], v237 offset:3072
	ds_read_b64_tr_b16 v[164:165], v237 offset:7168
	ds_read_b64_tr_b16 v[166:167], v237 offset:11264
	ds_read_b64_tr_b16 v[168:169], v237 offset:15360
	ds_read_b64_tr_b16 v[170:171], v237 offset:19456
	ds_read_b64_tr_b16 v[172:173], v237 offset:23552
	ds_read_b64_tr_b16 v[174:175], v237 offset:27648
	ds_read_b64_tr_b16 v[176:177], v237 offset:31744
	s_waitcnt lgkmcnt(8)
	v_mfma_f32_32x32x16_bf16 v[80:95], v[196:199], v[178:181], v[80:95]
	v_mfma_f32_32x32x16_bf16 v[80:95], v[200:203], v[182:185], v[80:95]
	v_mfma_f32_32x32x16_bf16 v[80:95], v[204:207], v[186:189], v[80:95]
	v_mfma_f32_32x32x16_bf16 v[80:95], v[208:211], v[190:193], v[80:95]
	ds_read_b64_tr_b16 v[178:179], v237 offset:3584
	ds_read_b64_tr_b16 v[180:181], v237 offset:7680
	ds_read_b64_tr_b16 v[182:183], v237 offset:11776
	ds_read_b64_tr_b16 v[184:185], v237 offset:15872
	ds_read_b64_tr_b16 v[186:187], v237 offset:19968
	ds_read_b64_tr_b16 v[188:189], v237 offset:24064
	ds_read_b64_tr_b16 v[190:191], v237 offset:28160
	ds_read_b64_tr_b16 v[192:193], v237 offset:32256
	s_waitcnt lgkmcnt(8)
	v_mfma_f32_32x32x16_bf16 v[98:113], v[196:199], v[162:165], v[98:113]
	v_mfma_f32_32x32x16_bf16 v[98:113], v[200:203], v[166:169], v[98:113]
	v_mfma_f32_32x32x16_bf16 v[98:113], v[204:207], v[170:173], v[98:113]
	v_mfma_f32_32x32x16_bf16 v[98:113], v[208:211], v[174:177], v[98:113]
	s_waitcnt lgkmcnt(0)
	v_mfma_f32_32x32x16_bf16 v[114:129], v[196:199], v[178:181], v[114:129]
	v_mfma_f32_32x32x16_bf16 v[114:129], v[200:203], v[182:185], v[114:129]
	v_mfma_f32_32x32x16_bf16 v[114:129], v[204:207], v[186:189], v[114:129]
	v_mfma_f32_32x32x16_bf16 v[114:129], v[208:211], v[190:193], v[114:129]
	s_waitcnt vmcnt(0)
	s_barrier
	s_cmp_le_u32 s13, 3
	s_cbranch_scc1 .Lam_nodma_b
	s_add_i32 m0, s39, 0xc000
	s_nop 0
	global_load_lds_dwordx4 v244, s[18:19]
	s_add_i32 m0, s39, 0xc400
	s_nop 0
	global_load_lds_dwordx4 v245, s[18:19]
	s_add_i32 m0, s47, 0xc000
	s_nop 0
	global_load_lds_dwordx4 v246, s[20:21]
	s_add_i32 m0, s47, 0xc400
	s_nop 0
	global_load_lds_dwordx4 v247, s[20:21]
	s_add_i32 m0, s47, 0xc800
	s_nop 0
	global_load_lds_dwordx4 v248, s[20:21]
	s_add_i32 m0, s47, 0xcc00
	s_nop 0
	global_load_lds_dwordx4 v249, s[20:21]
	s_add_u32 s18, s18, 0x40000
	s_addc_u32 s19, s19, 0
	s_add_u32 s20, s20, 0x40000
	s_addc_u32 s21, s21, 0
